# v70 + filter MLP matvecs broadcast the input unit via v_readlane (SGPR fmac operand) instead of ds_bpermute + waits; same fmac order
# baseline (speedup 1.0000x reference)
; #define GAS __attribute__((address_space(1)))
; __device__ __forceinline__ void pro_a(Frame& F, CArgs a, unsigned long long& tm_acc) {
;     ...
;                 float h = ((const GAS float*)a->in[I_FB1])[l * 64 + F.lane];
;                 for (int i = 0; i < 33; ++i) h += __shfl(zf, i) * ((const GAS float*)a->in[I_FW1])[((size_t)l * 33 + i) * 64 + F.lane];
;                 h = sinf(((const GAS float*)a->in[I_FF1])[l * 64 + F.lane] * h);
.LBB0_228:
	s_or_b64 exec, exec, s[10:11]
	s_mov_b32 s10, 0
	v_mov_b64_e32 v[10:11], v[4:5]
	s_waitcnt vmcnt(5)
	v_mov_b32_e32 v28, v12
	s_nop 1
	v_readlane_b32 s100, v2, 0
	v_fmac_f32_e32 v28, s100, v51
	v_readlane_b32 s101, v2, 1
	v_fmac_f32_e32 v28, s101, v52
	v_readlane_b32 s100, v2, 2
	v_fmac_f32_e32 v28, s100, v53
	v_readlane_b32 s101, v2, 3
	v_fmac_f32_e32 v28, s101, v54
	v_readlane_b32 s100, v2, 4
	v_fmac_f32_e32 v28, s100, v55
	v_readlane_b32 s101, v2, 5
	v_fmac_f32_e32 v28, s101, v56
	v_readlane_b32 s100, v2, 6
	v_fmac_f32_e32 v28, s100, v57
	v_readlane_b32 s101, v2, 7
	v_fmac_f32_e32 v28, s101, v58
	v_readlane_b32 s100, v2, 8
	v_fmac_f32_e32 v28, s100, v59
	v_readlane_b32 s101, v2, 9
	v_fmac_f32_e32 v28, s101, v60
	v_readlane_b32 s100, v2, 10
	v_fmac_f32_e32 v28, s100, v61
	v_readlane_b32 s101, v2, 11
	v_fmac_f32_e32 v28, s101, v62
	v_readlane_b32 s100, v2, 12
	v_fmac_f32_e32 v28, s100, v63
	v_readlane_b32 s101, v2, 13
	v_fmac_f32_e32 v28, s101, v64
	v_readlane_b32 s100, v2, 14
	v_fmac_f32_e32 v28, s100, v65
	v_readlane_b32 s101, v2, 15
	v_fmac_f32_e32 v28, s101, v66
	v_readlane_b32 s100, v2, 16
	v_fmac_f32_e32 v28, s100, v67
	v_readlane_b32 s101, v2, 17
	v_fmac_f32_e32 v28, s101, v68
	v_readlane_b32 s100, v2, 18
	v_fmac_f32_e32 v28, s100, v69
	v_readlane_b32 s101, v2, 19
	v_fmac_f32_e32 v28, s101, v70
	v_readlane_b32 s100, v2, 20
	v_fmac_f32_e32 v28, s100, v71
	v_readlane_b32 s101, v2, 21
	v_fmac_f32_e32 v28, s101, v72
	v_readlane_b32 s100, v2, 22
	v_fmac_f32_e32 v28, s100, v73
	v_readlane_b32 s101, v2, 23
	v_fmac_f32_e32 v28, s101, v74
	v_readlane_b32 s100, v2, 24
	v_fmac_f32_e32 v28, s100, v75
	v_readlane_b32 s101, v2, 25
	v_fmac_f32_e32 v28, s101, v76
	v_readlane_b32 s100, v2, 26
	v_fmac_f32_e32 v28, s100, v77
	v_readlane_b32 s101, v2, 27
	v_fmac_f32_e32 v28, s101, v78
	v_readlane_b32 s100, v2, 28
	v_fmac_f32_e32 v28, s100, v79
	v_readlane_b32 s101, v2, 29
	v_fmac_f32_e32 v28, s101, v80
	v_readlane_b32 s100, v2, 30
	v_fmac_f32_e32 v28, s100, v81
	v_readlane_b32 s101, v2, 31
	v_fmac_f32_e32 v28, s101, v82
	v_readlane_b32 s100, v2, 32
	v_fmac_f32_e32 v28, s100, v83
	v_mul_f32_e32 v10, v13, v28
	v_and_b32_e32 v11, 0x7fffffff, v10
	v_cmp_nlt_f32_e64 s[10:11], |v10|, s48
	s_and_saveexec_b64 s[12:13], s[10:11]
	s_xor_b64 s[22:23], exec, s[12:13]
	s_cbranch_execz .LBB0_232
	v_lshrrev_b32_e32 v2, 23, v11
	v_add_u32_e32 v2, 0xffffff88, v2
	v_cmp_lt_u32_e32 vcc, 63, v2
	s_nop 1
	v_cndmask_b32_e32 v28, 0, v24, vcc
	v_add_u32_e32 v2, v28, v2
	v_cmp_lt_u32_e64 s[10:11], 31, v2
	s_nop 1
	v_cndmask_b32_e64 v28, 0, v25, s[10:11]
	v_add_u32_e32 v2, v28, v2
	v_cmp_lt_u32_e64 s[12:13], 31, v2
	s_nop 1
	v_cndmask_b32_e64 v28, 0, v25, s[12:13]
	v_add_u32_e32 v42, v28, v2
	v_and_b32_e32 v2, 0x7fffff, v11
	v_or_b32_e32 v40, 0x800000, v2
	v_mad_u64_u32 v[28:29], s[14:15], v40, s49, 0
	v_mov_b32_e32 v2, v29
	v_mad_u64_u32 v[30:31], s[14:15], v40, s50, v[2:3]
	v_mov_b32_e32 v2, v31
	v_mad_u64_u32 v[32:33], s[14:15], v40, s51, v[2:3]
	v_mov_b32_e32 v2, v33
	v_mad_u64_u32 v[34:35], s[14:15], v40, s52, v[2:3]
	v_mov_b32_e32 v2, v35
	v_mad_u64_u32 v[36:37], s[14:15], v40, s53, v[2:3]
	v_mov_b32_e32 v2, v37
	v_mad_u64_u32 v[38:39], s[14:15], v40, s54, v[2:3]
	v_mov_b32_e32 v2, v39
	v_mad_u64_u32 v[40:41], s[14:15], v40, s55, v[2:3]
	v_cndmask_b32_e32 v29, v38, v34, vcc
	v_cndmask_b32_e32 v2, v40, v36, vcc
	v_cndmask_b32_e32 v33, v41, v38, vcc
	v_cndmask_b32_e64 v31, v2, v29, s[10:11]
	v_cndmask_b32_e64 v2, v33, v2, s[10:11]
	v_cndmask_b32_e32 v33, v36, v32, vcc
	v_cndmask_b32_e64 v29, v29, v33, s[10:11]
	v_cndmask_b32_e32 v30, v34, v30, vcc
	v_cndmask_b32_e64 v2, v2, v31, s[12:13]
	v_cndmask_b32_e64 v31, v31, v29, s[12:13]
	v_sub_u32_e32 v35, 32, v42
	v_cndmask_b32_e64 v33, v33, v30, s[10:11]
	v_alignbit_b32 v36, v2, v31, v35
	v_cmp_eq_u32_e64 s[14:15], 0, v42
	v_cndmask_b32_e64 v29, v29, v33, s[12:13]
	v_cndmask_b32_e32 v28, v32, v28, vcc
	v_cndmask_b32_e64 v2, v36, v2, s[14:15]
	v_alignbit_b32 v34, v31, v29, v35
	v_cndmask_b32_e64 v28, v30, v28, s[10:11]
	v_cndmask_b32_e64 v31, v34, v31, s[14:15]
	v_bfe_u32 v37, v2, 29, 1
	v_cndmask_b32_e64 v28, v33, v28, s[12:13]
	v_alignbit_b32 v34, v2, v31, 30
	v_sub_u32_e32 v38, 0, v37
	v_alignbit_b32 v30, v29, v28, v35
	v_xor_b32_e32 v34, v34, v38
	v_cndmask_b32_e64 v29, v30, v29, s[14:15]
	v_alignbit_b32 v30, v31, v29, 30
	v_ffbh_u32_e32 v31, v34
	v_min_u32_e32 v31, 32, v31
	v_alignbit_b32 v28, v29, v28, 30
	v_xor_b32_e32 v30, v30, v38
	v_sub_u32_e32 v32, 31, v31
	v_xor_b32_e32 v28, v28, v38
	v_alignbit_b32 v33, v34, v30, v32
	v_alignbit_b32 v28, v30, v28, v32
	v_alignbit_b32 v29, v33, v28, 9
	v_ffbh_u32_e32 v30, v29
	v_min_u32_e32 v30, 32, v30
	v_lshrrev_b32_e32 v36, 29, v2
	v_not_b32_e32 v32, v30
	v_alignbit_b32 v28, v29, v28, v32
	v_lshlrev_b32_e32 v29, 31, v36
	v_or_b32_e32 v32, 0x33000000, v29
	v_add_lshl_u32 v30, v30, v31, 23
	v_lshrrev_b32_e32 v28, 9, v28
	v_sub_u32_e32 v30, v32, v30
	v_or_b32_e32 v29, 0.5, v29
	v_lshlrev_b32_e32 v31, 23, v31
	v_or_b32_e32 v28, v30, v28
	v_lshrrev_b32_e32 v30, 9, v33
	v_sub_u32_e32 v29, v29, v31
	v_or_b32_e32 v29, v30, v29
	v_mul_f32_e32 v30, 0x3fc90fda, v29
	v_fma_f32 v31, v29, s56, -v30
	v_fmac_f32_e32 v31, 0x33a22168, v29
	v_fmac_f32_e32 v31, 0x3fc90fda, v28
	v_lshrrev_b32_e32 v2, 30, v2
	v_add_f32_e32 v28, v30, v31
	v_add_u32_e32 v2, v37, v2
; #define GAS __attribute__((address_space(1)))
; __device__ __forceinline__ void pro_a(Frame& F, CArgs a, unsigned long long& tm_acc) {
;     ...
;                 h = sinf(((const GAS float*)a->in[I_FF1])[l * 64 + F.lane] * h);
;                 float h2 = ((const GAS float*)a->in[I_FB2])[l * 64 + F.lane];
;                 for (int i = 0; i < 64; ++i) h2 += __shfl(h, i) * ((const GAS float*)a->in[I_FW2])[((size_t)l * 64 + i) * 64 + F.lane];
;                 h2 = sinf(((const GAS float*)a->in[I_FF2])[l * 64 + F.lane] * h2);
.LBB0_232:
	s_andn2_saveexec_b64 s[10:11], s[22:23]
	v_mul_f32_e64 v2, |v10|, s57
	v_rndne_f32_e32 v29, v2
	v_cvt_i32_f32_e32 v2, v29
	v_fma_f32 v28, v29, s58, |v10|
	v_fmac_f32_e32 v28, 0xb3a22168, v29
	v_fmac_f32_e32 v28, 0xa7c234c4, v29
	s_or_b64 exec, exec, s[10:11]
	v_mul_f32_e32 v29, v28, v28
	v_fmamk_f32 v30, v29, 0xb94c1982, v22
	v_fmaak_f32 v30, v29, v30, 0xbe2aaa9d
	v_mul_f32_e32 v30, v29, v30
	v_fmac_f32_e32 v28, v28, v30
	v_fmamk_f32 v30, v29, 0x37d75334, v23
	v_fmaak_f32 v30, v29, v30, 0x3d2aabf7
	v_fmaak_f32 v30, v29, v30, 0xbf000004
	v_fma_f32 v29, v29, v30, 1.0
	v_and_b32_e32 v30, 1, v2
	v_lshlrev_b32_e32 v2, 30, v2
	v_cmp_eq_u32_e32 vcc, 0, v30
	v_and_b32_e32 v2, 0x80000000, v2
	v_xor_b32_e32 v11, v11, v10
	v_cndmask_b32_e32 v28, v29, v28, vcc
	v_xor_b32_e32 v2, v11, v2
	v_xor_b32_e32 v2, v2, v28
	v_cmp_class_f32_e64 vcc, v10, s60
	s_mov_b32 s10, 0
	v_mov_b64_e32 v[10:11], v[6:7]
	v_cndmask_b32_e32 v2, v27, v2, vcc
	v_mov_b32_e32 v28, v14
	s_nop 1
	v_readlane_b32 s101, v2, 0
	v_fmac_f32_e32 v28, s101, v102
	v_readlane_b32 s100, v2, 1
	v_fmac_f32_e32 v28, s100, v103
	v_readlane_b32 s101, v2, 2
	v_fmac_f32_e32 v28, s101, v104
	v_readlane_b32 s100, v2, 3
	v_fmac_f32_e32 v28, s100, v105
	v_readlane_b32 s101, v2, 4
	v_fmac_f32_e32 v28, s101, v106
	v_readlane_b32 s100, v2, 5
	v_fmac_f32_e32 v28, s100, v107
	v_readlane_b32 s101, v2, 6
	v_fmac_f32_e32 v28, s101, v108
	v_readlane_b32 s100, v2, 7
	v_fmac_f32_e32 v28, s100, v109
	v_readlane_b32 s101, v2, 8
	v_fmac_f32_e32 v28, s101, v110
	v_readlane_b32 s100, v2, 9
	v_fmac_f32_e32 v28, s100, v111
	v_readlane_b32 s101, v2, 10
	v_fmac_f32_e32 v28, s101, v112
	v_readlane_b32 s100, v2, 11
	v_fmac_f32_e32 v28, s100, v113
	v_readlane_b32 s101, v2, 12
	v_fmac_f32_e32 v28, s101, v114
	v_readlane_b32 s100, v2, 13
	v_fmac_f32_e32 v28, s100, v115
	v_readlane_b32 s101, v2, 14
	v_fmac_f32_e32 v28, s101, v116
	v_readlane_b32 s100, v2, 15
	v_fmac_f32_e32 v28, s100, v117
	v_readlane_b32 s101, v2, 16
	v_fmac_f32_e32 v28, s101, v118
	v_readlane_b32 s100, v2, 17
	v_fmac_f32_e32 v28, s100, v119
	v_readlane_b32 s101, v2, 18
	v_fmac_f32_e32 v28, s101, v120
	v_readlane_b32 s100, v2, 19
	v_fmac_f32_e32 v28, s100, v121
	v_readlane_b32 s101, v2, 20
	v_fmac_f32_e32 v28, s101, v122
	v_readlane_b32 s100, v2, 21
	v_fmac_f32_e32 v28, s100, v123
	v_readlane_b32 s101, v2, 22
	v_fmac_f32_e32 v28, s101, v124
	v_readlane_b32 s100, v2, 23
	v_fmac_f32_e32 v28, s100, v125
	v_readlane_b32 s101, v2, 24
	v_fmac_f32_e32 v28, s101, v126
	v_readlane_b32 s100, v2, 25
	v_fmac_f32_e32 v28, s100, v127
	v_readlane_b32 s101, v2, 26
	v_fmac_f32_e32 v28, s101, v128
	v_readlane_b32 s100, v2, 27
	v_fmac_f32_e32 v28, s100, v129
	v_readlane_b32 s101, v2, 28
	v_fmac_f32_e32 v28, s101, v130
	v_readlane_b32 s100, v2, 29
	v_fmac_f32_e32 v28, s100, v131
	v_readlane_b32 s101, v2, 30
	v_fmac_f32_e32 v28, s101, v132
	v_readlane_b32 s100, v2, 31
	v_fmac_f32_e32 v28, s100, v133
	v_readlane_b32 s101, v2, 32
	v_fmac_f32_e32 v28, s101, v134
	v_readlane_b32 s100, v2, 33
	v_fmac_f32_e32 v28, s100, v135
	v_readlane_b32 s101, v2, 34
	v_fmac_f32_e32 v28, s101, v136
	v_readlane_b32 s100, v2, 35
	v_fmac_f32_e32 v28, s100, v137
	v_readlane_b32 s101, v2, 36
	v_fmac_f32_e32 v28, s101, v138
	v_readlane_b32 s100, v2, 37
	v_fmac_f32_e32 v28, s100, v139
	v_readlane_b32 s101, v2, 38
	v_fmac_f32_e32 v28, s101, v140
	v_readlane_b32 s100, v2, 39
	v_fmac_f32_e32 v28, s100, v141
	v_readlane_b32 s101, v2, 40
	v_fmac_f32_e32 v28, s101, v142
	v_readlane_b32 s100, v2, 41
	v_fmac_f32_e32 v28, s100, v143
	v_readlane_b32 s101, v2, 42
	v_fmac_f32_e32 v28, s101, v144
	v_readlane_b32 s100, v2, 43
	v_fmac_f32_e32 v28, s100, v145
	v_readlane_b32 s101, v2, 44
	v_fmac_f32_e32 v28, s101, v146
	v_readlane_b32 s100, v2, 45
	v_fmac_f32_e32 v28, s100, v147
	v_readlane_b32 s101, v2, 46
	v_fmac_f32_e32 v28, s101, v148
	v_readlane_b32 s100, v2, 47
	v_fmac_f32_e32 v28, s100, v149
	v_readlane_b32 s101, v2, 48
	v_fmac_f32_e32 v28, s101, v150
	v_readlane_b32 s100, v2, 49
	v_fmac_f32_e32 v28, s100, v151
	v_readlane_b32 s101, v2, 50
	v_fmac_f32_e32 v28, s101, v152
	v_readlane_b32 s100, v2, 51
	v_fmac_f32_e32 v28, s100, v153
	v_readlane_b32 s101, v2, 52
	v_fmac_f32_e32 v28, s101, v154
	v_readlane_b32 s100, v2, 53
	v_fmac_f32_e32 v28, s100, v155
	v_readlane_b32 s101, v2, 54
	v_fmac_f32_e32 v28, s101, v156
	v_readlane_b32 s100, v2, 55
	v_fmac_f32_e32 v28, s100, v157
	v_readlane_b32 s101, v2, 56
	v_fmac_f32_e32 v28, s101, v158
	v_readlane_b32 s100, v2, 57
	v_fmac_f32_e32 v28, s100, v159
	v_readlane_b32 s101, v2, 58
	v_fmac_f32_e32 v28, s101, v160
	v_readlane_b32 s100, v2, 59
	v_fmac_f32_e32 v28, s100, v161
	v_readlane_b32 s101, v2, 60
	v_fmac_f32_e32 v28, s101, v162
	v_readlane_b32 s100, v2, 61
	v_fmac_f32_e32 v28, s100, v163
	v_readlane_b32 s101, v2, 62
	v_fmac_f32_e32 v28, s101, v164
	v_readlane_b32 s100, v2, 63
	v_fmac_f32_e32 v28, s100, v165
	v_mul_f32_e32 v10, v15, v28
	v_and_b32_e32 v11, 0x7fffffff, v10
	v_cmp_nlt_f32_e64 s[10:11], |v10|, s48
	s_and_saveexec_b64 s[12:13], s[10:11]
	s_xor_b64 s[22:23], exec, s[12:13]
	s_cbranch_execz .LBB0_238
; #define GAS __attribute__((address_space(1)))
; __device__ __forceinline__ void pro_a(Frame& F, CArgs a, unsigned long long& tm_acc) {
;     ...
;                 h2 = sinf(((const GAS float*)a->in[I_FF2])[l * 64 + F.lane] * h2);
;                 float h3 = ((const GAS float*)a->in[I_FB3])[l * 64 + F.lane];
;                 for (int i = 0; i < 64; ++i) h3 += __shfl(h2, i) * ((const GAS float*)a->in[I_FW3])[((size_t)l * 64 + i) * 64 + F.lane];
	v_lshrrev_b32_e32 v2, 23, v11
	v_add_u32_e32 v2, 0xffffff88, v2
	v_cmp_lt_u32_e32 vcc, 63, v2
	s_nop 1
	v_cndmask_b32_e32 v28, 0, v24, vcc
	v_add_u32_e32 v2, v28, v2
	v_cmp_lt_u32_e64 s[10:11], 31, v2
	s_nop 1
	v_cndmask_b32_e64 v28, 0, v25, s[10:11]
	v_add_u32_e32 v2, v28, v2
	v_cmp_lt_u32_e64 s[12:13], 31, v2
	s_nop 1
	v_cndmask_b32_e64 v28, 0, v25, s[12:13]
	v_add_u32_e32 v42, v28, v2
	v_and_b32_e32 v2, 0x7fffff, v11
	v_or_b32_e32 v40, 0x800000, v2
	v_mad_u64_u32 v[28:29], s[14:15], v40, s49, 0
	v_mov_b32_e32 v2, v29
	v_mad_u64_u32 v[30:31], s[14:15], v40, s50, v[2:3]
	v_mov_b32_e32 v2, v31
	v_mad_u64_u32 v[32:33], s[14:15], v40, s51, v[2:3]
	v_mov_b32_e32 v2, v33
	v_mad_u64_u32 v[34:35], s[14:15], v40, s52, v[2:3]
	v_mov_b32_e32 v2, v35
	v_mad_u64_u32 v[36:37], s[14:15], v40, s53, v[2:3]
	v_mov_b32_e32 v2, v37
	v_mad_u64_u32 v[38:39], s[14:15], v40, s54, v[2:3]
	v_mov_b32_e32 v2, v39
	v_mad_u64_u32 v[40:41], s[14:15], v40, s55, v[2:3]
	v_cndmask_b32_e32 v29, v38, v34, vcc
	v_cndmask_b32_e32 v2, v40, v36, vcc
	v_cndmask_b32_e32 v33, v41, v38, vcc
	v_cndmask_b32_e64 v31, v2, v29, s[10:11]
	v_cndmask_b32_e64 v2, v33, v2, s[10:11]
	v_cndmask_b32_e32 v33, v36, v32, vcc
	v_cndmask_b32_e64 v29, v29, v33, s[10:11]
	v_cndmask_b32_e32 v30, v34, v30, vcc
	v_cndmask_b32_e64 v2, v2, v31, s[12:13]
	v_cndmask_b32_e64 v31, v31, v29, s[12:13]
	v_sub_u32_e32 v35, 32, v42
	v_cndmask_b32_e64 v33, v33, v30, s[10:11]
	v_alignbit_b32 v36, v2, v31, v35
	v_cmp_eq_u32_e64 s[14:15], 0, v42
	v_cndmask_b32_e64 v29, v29, v33, s[12:13]
	v_cndmask_b32_e32 v28, v32, v28, vcc
	v_cndmask_b32_e64 v2, v36, v2, s[14:15]
	v_alignbit_b32 v34, v31, v29, v35
	v_cndmask_b32_e64 v28, v30, v28, s[10:11]
	v_cndmask_b32_e64 v31, v34, v31, s[14:15]
	v_bfe_u32 v37, v2, 29, 1
	v_cndmask_b32_e64 v28, v33, v28, s[12:13]
	v_alignbit_b32 v34, v2, v31, 30
	v_sub_u32_e32 v38, 0, v37
	v_alignbit_b32 v30, v29, v28, v35
	v_xor_b32_e32 v34, v34, v38
	v_cndmask_b32_e64 v29, v30, v29, s[14:15]
	v_alignbit_b32 v30, v31, v29, 30
	v_ffbh_u32_e32 v31, v34
	v_min_u32_e32 v31, 32, v31
	v_alignbit_b32 v28, v29, v28, 30
	v_xor_b32_e32 v30, v30, v38
	v_sub_u32_e32 v32, 31, v31
	v_xor_b32_e32 v28, v28, v38
	v_alignbit_b32 v33, v34, v30, v32
	v_alignbit_b32 v28, v30, v28, v32
	v_alignbit_b32 v29, v33, v28, 9
	v_ffbh_u32_e32 v30, v29
	v_min_u32_e32 v30, 32, v30
	v_lshrrev_b32_e32 v36, 29, v2
	v_not_b32_e32 v32, v30
	v_alignbit_b32 v28, v29, v28, v32
	v_lshlrev_b32_e32 v29, 31, v36
	v_or_b32_e32 v32, 0x33000000, v29
	v_add_lshl_u32 v30, v30, v31, 23
	v_lshrrev_b32_e32 v28, 9, v28
	v_sub_u32_e32 v30, v32, v30
	v_or_b32_e32 v29, 0.5, v29
	v_lshlrev_b32_e32 v31, 23, v31
	v_or_b32_e32 v28, v30, v28
	v_lshrrev_b32_e32 v30, 9, v33
	v_sub_u32_e32 v29, v29, v31
	v_or_b32_e32 v29, v30, v29
	v_mul_f32_e32 v30, 0x3fc90fda, v29
	v_fma_f32 v31, v29, s56, -v30
	v_fmac_f32_e32 v31, 0x33a22168, v29
	v_fmac_f32_e32 v31, 0x3fc90fda, v28
	v_lshrrev_b32_e32 v2, 30, v2
	v_add_f32_e32 v28, v30, v31
	v_add_u32_e32 v2, v37, v2
.LBB0_238:
	s_andn2_saveexec_b64 s[10:11], s[22:23]
	v_mul_f32_e64 v2, |v10|, s57
	v_rndne_f32_e32 v29, v2
	v_cvt_i32_f32_e32 v2, v29
	v_fma_f32 v28, v29, s58, |v10|
	v_fmac_f32_e32 v28, 0xb3a22168, v29
	v_fmac_f32_e32 v28, 0xa7c234c4, v29
	s_or_b64 exec, exec, s[10:11]
	v_mul_f32_e32 v29, v28, v28
	v_fmamk_f32 v30, v29, 0xb94c1982, v22
	v_fmaak_f32 v30, v29, v30, 0xbe2aaa9d
	v_mul_f32_e32 v30, v29, v30
	v_fmac_f32_e32 v28, v28, v30
	v_fmamk_f32 v30, v29, 0x37d75334, v23
	v_fmaak_f32 v30, v29, v30, 0x3d2aabf7
	v_fmaak_f32 v30, v29, v30, 0xbf000004
	v_fma_f32 v29, v29, v30, 1.0
	v_and_b32_e32 v30, 1, v2
	v_lshlrev_b32_e32 v2, 30, v2
	v_cmp_eq_u32_e32 vcc, 0, v30
	v_and_b32_e32 v2, 0x80000000, v2
	v_xor_b32_e32 v11, v11, v10
	v_cndmask_b32_e32 v28, v29, v28, vcc
	v_xor_b32_e32 v2, v11, v2
	v_xor_b32_e32 v2, v2, v28
	v_cmp_class_f32_e64 vcc, v10, s60
	s_mov_b32 s10, 0
	v_mov_b64_e32 v[10:11], v[8:9]
	v_cndmask_b32_e32 v2, v27, v2, vcc
	v_mov_b32_e32 v28, v16
	s_nop 1
	v_readlane_b32 s101, v2, 0
	v_fmac_f32_e32 v28, s101, v166
	v_readlane_b32 s100, v2, 1
	v_fmac_f32_e32 v28, s100, v167
	v_readlane_b32 s101, v2, 2
	v_fmac_f32_e32 v28, s101, v168
	v_readlane_b32 s100, v2, 3
	v_fmac_f32_e32 v28, s100, v169
	v_readlane_b32 s101, v2, 4
	v_fmac_f32_e32 v28, s101, v170
	v_readlane_b32 s100, v2, 5
	v_fmac_f32_e32 v28, s100, v171
	v_readlane_b32 s101, v2, 6
	v_fmac_f32_e32 v28, s101, v172
	v_readlane_b32 s100, v2, 7
	v_fmac_f32_e32 v28, s100, v173
	v_readlane_b32 s101, v2, 8
	v_fmac_f32_e32 v28, s101, v174
	v_readlane_b32 s100, v2, 9
	v_fmac_f32_e32 v28, s100, v175
	v_readlane_b32 s101, v2, 10
	v_fmac_f32_e32 v28, s101, v176
	v_readlane_b32 s100, v2, 11
	v_fmac_f32_e32 v28, s100, v177
	v_readlane_b32 s101, v2, 12
	v_fmac_f32_e32 v28, s101, v178
	v_readlane_b32 s100, v2, 13
	v_fmac_f32_e32 v28, s100, v179
	v_readlane_b32 s101, v2, 14
	v_fmac_f32_e32 v28, s101, v180
	v_readlane_b32 s100, v2, 15
	v_fmac_f32_e32 v28, s100, v181
	v_readlane_b32 s101, v2, 16
	v_fmac_f32_e32 v28, s101, v182
	v_readlane_b32 s100, v2, 17
	v_fmac_f32_e32 v28, s100, v183
	v_readlane_b32 s101, v2, 18
	v_fmac_f32_e32 v28, s101, v184
	v_readlane_b32 s100, v2, 19
	v_fmac_f32_e32 v28, s100, v185
	v_readlane_b32 s101, v2, 20
	v_fmac_f32_e32 v28, s101, v186
	v_readlane_b32 s100, v2, 21
	v_fmac_f32_e32 v28, s100, v187
	v_readlane_b32 s101, v2, 22
	v_fmac_f32_e32 v28, s101, v188
	v_readlane_b32 s100, v2, 23
	v_fmac_f32_e32 v28, s100, v189
	v_readlane_b32 s101, v2, 24
	v_fmac_f32_e32 v28, s101, v190
	v_readlane_b32 s100, v2, 25
	v_fmac_f32_e32 v28, s100, v191
; #define GAS __attribute__((address_space(1)))
; __device__ __forceinline__ void pro_a(Frame& F, CArgs a, unsigned long long& tm_acc) {
;     ...
;                 for (int i = 0; i < 64; ++i) h3 += __shfl(h2, i) * ((const GAS float*)a->in[I_FW3])[((size_t)l * 64 + i) * 64 + F.lane];
;                 h3 = sinf(((const GAS float*)a->in[I_FF3])[l * 64 + F.lane] * h3);
	v_readlane_b32 s101, v2, 26
	v_fmac_f32_e32 v28, s101, v192
	v_readlane_b32 s100, v2, 27
	v_fmac_f32_e32 v28, s100, v193
	v_readlane_b32 s101, v2, 28
	v_fmac_f32_e32 v28, s101, v194
	v_readlane_b32 s100, v2, 29
	v_fmac_f32_e32 v28, s100, v195
	v_readlane_b32 s101, v2, 30
	v_fmac_f32_e32 v28, s101, v196
	v_readlane_b32 s100, v2, 31
	v_fmac_f32_e32 v28, s100, v197
	v_readlane_b32 s101, v2, 32
	v_fmac_f32_e32 v28, s101, v198
	v_readlane_b32 s100, v2, 33
	v_fmac_f32_e32 v28, s100, v199
	v_readlane_b32 s101, v2, 34
	v_fmac_f32_e32 v28, s101, v200
	v_readlane_b32 s100, v2, 35
	v_fmac_f32_e32 v28, s100, v201
	v_readlane_b32 s101, v2, 36
	v_fmac_f32_e32 v28, s101, v202
	v_readlane_b32 s100, v2, 37
	v_fmac_f32_e32 v28, s100, v203
	v_readlane_b32 s101, v2, 38
	v_fmac_f32_e32 v28, s101, v204
	v_readlane_b32 s100, v2, 39
	v_fmac_f32_e32 v28, s100, v205
	v_readlane_b32 s101, v2, 40
	v_fmac_f32_e32 v28, s101, v206
	v_readlane_b32 s100, v2, 41
	v_fmac_f32_e32 v28, s100, v207
	v_readlane_b32 s101, v2, 42
	v_fmac_f32_e32 v28, s101, v208
	v_readlane_b32 s100, v2, 43
	v_fmac_f32_e32 v28, s100, v209
	v_readlane_b32 s101, v2, 44
	v_fmac_f32_e32 v28, s101, v210
	v_readlane_b32 s100, v2, 45
	v_fmac_f32_e32 v28, s100, v211
	v_readlane_b32 s101, v2, 46
	v_fmac_f32_e32 v28, s101, v212
	v_readlane_b32 s100, v2, 47
	v_fmac_f32_e32 v28, s100, v213
	v_readlane_b32 s101, v2, 48
	v_fmac_f32_e32 v28, s101, v214
	v_readlane_b32 s100, v2, 49
	v_fmac_f32_e32 v28, s100, v215
	v_readlane_b32 s101, v2, 50
	v_fmac_f32_e32 v28, s101, v216
	v_readlane_b32 s100, v2, 51
	v_fmac_f32_e32 v28, s100, v217
	v_readlane_b32 s101, v2, 52
	v_fmac_f32_e32 v28, s101, v218
	v_readlane_b32 s100, v2, 53
	v_fmac_f32_e32 v28, s100, v219
	v_readlane_b32 s101, v2, 54
	v_fmac_f32_e32 v28, s101, v220
	v_readlane_b32 s100, v2, 55
	v_fmac_f32_e32 v28, s100, v221
	v_readlane_b32 s101, v2, 56
	v_fmac_f32_e32 v28, s101, v222
	v_readlane_b32 s100, v2, 57
	v_fmac_f32_e32 v28, s100, v223
	v_readlane_b32 s101, v2, 58
	v_fmac_f32_e32 v28, s101, v224
	v_readlane_b32 s100, v2, 59
	v_fmac_f32_e32 v28, s100, v225
	v_readlane_b32 s101, v2, 60
	v_fmac_f32_e32 v28, s101, v226
	v_readlane_b32 s100, v2, 61
	v_fmac_f32_e32 v28, s100, v227
	v_readlane_b32 s101, v2, 62
	v_fmac_f32_e32 v28, s101, v228
	v_readlane_b32 s100, v2, 63
	v_fmac_f32_e32 v28, s100, v229
	v_mul_f32_e32 v10, v17, v28
	v_and_b32_e32 v11, 0x7fffffff, v10
	v_cmp_nlt_f32_e64 s[10:11], |v10|, s48
	s_and_saveexec_b64 s[12:13], s[10:11]
	s_xor_b64 s[22:23], exec, s[12:13]
	s_cbranch_execz .LBB0_244
	v_lshrrev_b32_e32 v2, 23, v11
	v_add_u32_e32 v2, 0xffffff88, v2
	v_cmp_lt_u32_e32 vcc, 63, v2
	s_nop 1
	v_cndmask_b32_e32 v28, 0, v24, vcc
	v_add_u32_e32 v2, v28, v2
	v_cmp_lt_u32_e64 s[10:11], 31, v2
	s_nop 1
	v_cndmask_b32_e64 v28, 0, v25, s[10:11]
	v_add_u32_e32 v2, v28, v2
	v_cmp_lt_u32_e64 s[12:13], 31, v2
	s_nop 1
	v_cndmask_b32_e64 v28, 0, v25, s[12:13]
	v_add_u32_e32 v42, v28, v2
	v_and_b32_e32 v2, 0x7fffff, v11
	v_or_b32_e32 v40, 0x800000, v2
	v_mad_u64_u32 v[28:29], s[14:15], v40, s49, 0
	v_mov_b32_e32 v2, v29
	v_mad_u64_u32 v[30:31], s[14:15], v40, s50, v[2:3]
	v_mov_b32_e32 v2, v31
	v_mad_u64_u32 v[32:33], s[14:15], v40, s51, v[2:3]
	v_mov_b32_e32 v2, v33
	v_mad_u64_u32 v[34:35], s[14:15], v40, s52, v[2:3]
	v_mov_b32_e32 v2, v35
	v_mad_u64_u32 v[36:37], s[14:15], v40, s53, v[2:3]
	v_mov_b32_e32 v2, v37
	v_mad_u64_u32 v[38:39], s[14:15], v40, s54, v[2:3]
	v_mov_b32_e32 v2, v39
	v_mad_u64_u32 v[40:41], s[14:15], v40, s55, v[2:3]
	v_cndmask_b32_e32 v29, v38, v34, vcc
	v_cndmask_b32_e32 v2, v40, v36, vcc
	v_cndmask_b32_e32 v33, v41, v38, vcc
	v_cndmask_b32_e64 v31, v2, v29, s[10:11]
	v_cndmask_b32_e64 v2, v33, v2, s[10:11]
	v_cndmask_b32_e32 v33, v36, v32, vcc
	v_cndmask_b32_e64 v29, v29, v33, s[10:11]
	v_cndmask_b32_e32 v30, v34, v30, vcc
	v_cndmask_b32_e64 v2, v2, v31, s[12:13]
	v_cndmask_b32_e64 v31, v31, v29, s[12:13]
	v_sub_u32_e32 v35, 32, v42
	v_cndmask_b32_e64 v33, v33, v30, s[10:11]
	v_alignbit_b32 v36, v2, v31, v35
	v_cmp_eq_u32_e64 s[14:15], 0, v42
	v_cndmask_b32_e64 v29, v29, v33, s[12:13]
	v_cndmask_b32_e32 v28, v32, v28, vcc
	v_cndmask_b32_e64 v2, v36, v2, s[14:15]
	v_alignbit_b32 v34, v31, v29, v35
	v_cndmask_b32_e64 v28, v30, v28, s[10:11]
	v_cndmask_b32_e64 v31, v34, v31, s[14:15]
	v_bfe_u32 v37, v2, 29, 1
	v_cndmask_b32_e64 v28, v33, v28, s[12:13]
	v_alignbit_b32 v34, v2, v31, 30
	v_sub_u32_e32 v38, 0, v37
	v_alignbit_b32 v30, v29, v28, v35
	v_xor_b32_e32 v34, v34, v38
	v_cndmask_b32_e64 v29, v30, v29, s[14:15]
	v_alignbit_b32 v30, v31, v29, 30
	v_ffbh_u32_e32 v31, v34
	v_min_u32_e32 v31, 32, v31
	v_alignbit_b32 v28, v29, v28, 30
	v_xor_b32_e32 v30, v30, v38
	v_sub_u32_e32 v32, 31, v31
	v_xor_b32_e32 v28, v28, v38
	v_alignbit_b32 v33, v34, v30, v32
	v_alignbit_b32 v28, v30, v28, v32
	v_alignbit_b32 v29, v33, v28, 9
	v_ffbh_u32_e32 v30, v29
	v_min_u32_e32 v30, 32, v30
	v_lshrrev_b32_e32 v36, 29, v2
	v_not_b32_e32 v32, v30
	v_alignbit_b32 v28, v29, v28, v32
	v_lshlrev_b32_e32 v29, 31, v36
	v_or_b32_e32 v32, 0x33000000, v29
	v_add_lshl_u32 v30, v30, v31, 23
	v_lshrrev_b32_e32 v28, 9, v28
	v_sub_u32_e32 v30, v32, v30
	v_or_b32_e32 v29, 0.5, v29
	v_lshlrev_b32_e32 v31, 23, v31
	v_or_b32_e32 v28, v30, v28
	v_lshrrev_b32_e32 v30, 9, v33
	v_sub_u32_e32 v29, v29, v31
	v_or_b32_e32 v29, v30, v29
	v_mul_f32_e32 v30, 0x3fc90fda, v29
	v_fma_f32 v31, v29, s56, -v30
	v_fmac_f32_e32 v31, 0x33a22168, v29
	v_fmac_f32_e32 v31, 0x3fc90fda, v28
	v_lshrrev_b32_e32 v2, 30, v2
	v_add_f32_e32 v28, v30, v31
	v_add_u32_e32 v2, v37, v2
